# phase C stage 1: jump directly to the single matching j per i instead of scanning all 36 (i,j) pairs with a skip test
# speedup vs baseline: 1.0094x; 1.0060x over previous
; #define LAS __attribute__((address_space(3)))
; DI unsigned pk2(float lo, float hi) { const f32x2_t v = {lo, hi}; const bf16x2_t b = __builtin_convertvector(v, bf16x2_t); return __builtin_bit_cast(unsigned, b); }
; DI float bf_lo(unsigned u) { return __uint_as_float(u << 16); }
; DI float bf_hi(unsigned u) { return __uint_as_float(u & 0xffff0000u); }
; DI void hgrn_phase_c(const Params& p, LAS unsigned char* lds) {
;     ...
;         {
;             int cnt = 0;
;             for (int i = 0; i < 8; ++i)
;                 for (int j = 0; j <= i; ++j, ++cnt) {
;                     if ((cnt & 7) != wsc) continue;
;                     f32x4 acc = (f32x4){0.f, 0.f, 0.f, 0.f};
; #pragma unroll
;                     for (int ks = 0; ks < 4; ++ks) {
;                         const bf16x8 kf = *(LAS const bf16x8*)(lds + R2 + (16 * j + l15) * RS + (32 * ks + 8 * g4) * 2);
;                         bf16x8 qf = *(LAS const bf16x8*)(lds + R1 + (16 * i + l15) * RS + (32 * ks + 8 * g4) * 2);
;                         if (i != j) {
;                             LAS const float* ep = (LAS const float*)(lds + OFF_ET) + (i * (i - 1) / 2 + j) * 128 + 32 * ks + 8 * g4;
;                             const f32x4 e0 = *(LAS const f32x4*)ep, e1 = *(LAS const f32x4*)(ep + 4);
;                             const u32x4 qq = __builtin_bit_cast(u32x4, qf);
;                             u32x4 ow;
;                             ow.x = pk2(bf_lo(qq.x) * e0[0], bf_hi(qq.x) * e0[1]);
;                             ow.y = pk2(bf_lo(qq.y) * e0[2], bf_hi(qq.y) * e0[3]);
;                             ow.z = pk2(bf_lo(qq.z) * e1[0], bf_hi(qq.z) * e1[1]);
;                             ow.w = pk2(bf_lo(qq.w) * e1[2], bf_hi(qq.w) * e1[3]);
;                             qf = __builtin_bit_cast(bf16x8, ow);
;                         }
;                         acc = __builtin_amdgcn_mfma_f32_16x16x32_bf16(kf, qf, acc, 0, 0, 0);
;                     }
;                     if (i == j) {
; #pragma unroll
;                         for (int jj = 0; jj < 4; ++jj) acc[jj] = (4 * g4 + jj <= l15) ? acc[jj] : 0.f;
;                     }
;                     u32x2 o; o.x = pk2(acc[0], acc[1]); o.y = pk2(acc[2], acc[3]);
;                     *(LAS u32x2*)(lds + R3 + (16 * i + l15) * RS + (16 * j + 4 * g4) * 2) = o;
;                 }
.LBB0_435:
	s_add_i32 s0, s3, -1
	s_mul_i32 s0, s0, s3
	s_lshr_b32 s1, s0, 31
	s_add_i32 s0, s0, s1
	v_lshl_or_b32 v48, s3, 4, v137
	s_lshl_b32 s0, s0, 8
	v_mul_lo_u32 v48, v48, s70
	s_and_b32 s0, s0, 0xfffffe00
	v_or_b32_e32 v170, s0, v153
	s_add_i32 s58, s3, 1
	v_add_u32_e32 v171, v148, v48
	v_mov_b32_e32 v172, v154
	v_mov_b32_e32 v173, v169
	s_sub_i32 s59, s35, s97
	s_and_b32 s59, s59, 7
	s_cmp_gt_u32 s59, s3
	s_cbranch_scc1 .LBB0_434
	s_lshl_b32 s0, s59, 5
	v_add_u32_e32 v173, s0, v173
	s_lshl_b32 s0, s59, 9
	v_add_u32_e32 v170, s0, v170
	s_mul_i32 s0, s59, 0x1100
	v_add_u32_e32 v172, s0, v172
	s_branch .Lc_s1_body
.LBB0_436:
	s_waitcnt lgkmcnt(1)
	v_mfma_f32_16x16x32_bf16 v[48:51], v[52:55], v[64:67], v[48:51]
	s_nop 7
	v_cndmask_b32_e64 v52, v48, 0, s[12:13]
	v_cndmask_b32_e64 v53, 0, v49, s[14:15]
	v_cndmask_b32_e64 v54, v50, 0, s[16:17]
	v_cndmask_b32_e64 v55, v51, 0, s[18:19]
	v_cndmask_b32_e64 v51, v51, v55, s[20:21]
	v_cndmask_b32_e64 v50, v50, v54, s[20:21]
	v_cndmask_b32_e64 v49, v49, v53, s[20:21]
	v_cndmask_b32_e64 v48, v48, v52, s[20:21]
	v_cvt_pk_bf16_f32 v48, v48, v49
	v_cvt_pk_bf16_f32 v49, v50, v51
	v_add_u32_e32 v50, 0, v173
	ds_write_b64 v50, v[48:49]
	s_branch .LBB0_434
.Lc_s1_body:
	v_add_u32_e32 v175, 0, v172
	ds_read_b128 v[48:51], v175
	ds_read_b128 v[52:55], v171
	s_cmp_eq_u32 s3, s59
	s_cselect_b64 s[20:21], -1, 0
	s_cmp_lg_u32 s3, s59
	s_cselect_b64 s[0:1], -1, 0
	v_add_u32_e32 v174, 0, v170
	s_mov_b64 s[66:67], -1
	s_and_b64 vcc, exec, s[0:1]
	s_cbranch_vccz .LBB0_441
	s_waitcnt lgkmcnt(3)
	v_add_u32_e32 v56, 0x1c800, v174
	ds_read_b128 v[56:59], v56
	v_add_u32_e32 v64, 0x1c810, v174
	ds_read_b128 v[64:67], v64
	s_waitcnt lgkmcnt(2)
	v_lshlrev_b32_e32 v178, 16, v52
	v_and_b32_e32 v179, 0xffff0000, v52
	s_waitcnt lgkmcnt(1)
	v_pk_mul_f32 v[56:57], v[56:57], v[178:179]
	v_lshlrev_b32_e32 v178, 16, v53
	v_and_b32_e32 v179, 0xffff0000, v53
	v_pk_mul_f32 v[58:59], v[58:59], v[178:179]
	v_cvt_pk_bf16_f32 v56, v56, v57
	v_cvt_pk_bf16_f32 v57, v58, v59
	v_lshlrev_b32_e32 v58, 16, v54
	v_and_b32_e32 v59, 0xffff0000, v54
	s_waitcnt lgkmcnt(0)
	v_pk_mul_f32 v[58:59], v[64:65], v[58:59]
	v_lshlrev_b32_e32 v64, 16, v55
	v_and_b32_e32 v65, 0xffff0000, v55
	v_pk_mul_f32 v[64:65], v[66:67], v[64:65]
	v_cvt_pk_bf16_f32 v58, v58, v59
	v_cvt_pk_bf16_f32 v59, v64, v65
	s_mov_b64 s[66:67], 0
